# M1 conv tasks of wave 0 in workgroups 0..31 (the ones with the extra sample-row token task) moved to wave 1
# speedup vs baseline: 1.0120x; 1.0007x over previous
.LBB0_318:
	s_or_b64 exec, exec, s[0:1]
	v_readlane_b32 s8, v252, 18
	s_mov_b32 s0, s89
	v_readlane_b32 s9, v252, 19
	v_readlane_b32 s10, v252, 20
	v_readlane_b32 s11, v252, 21
	v_readlane_b32 s12, v252, 22
	v_readlane_b32 s13, v252, 23
	v_readlane_b32 s14, v252, 24
	v_readlane_b32 s15, v252, 25
	v_readlane_b32 s16, v252, 26
	v_readlane_b32 s17, v252, 27
	v_readlane_b32 s18, v252, 28
	v_readlane_b32 s19, v252, 29
	s_barrier
	s_mul_i32 s42, s56, 0x300
	v_readlane_b32 s20, v252, 30
	v_readlane_b32 s21, v252, 31
	v_readlane_b32 s22, v252, 32
	v_readlane_b32 s23, v252, 33
	s_mov_b64 s[8:9], s[12:13]
	s_lshl_b32 s2, s0, 6
	s_lshl_b64 s[0:1], s[42:43], 2
	s_mov_b64 s[10:11], s[14:15]
	s_mov_b64 s[12:13], s[16:17]
	s_mov_b64 s[14:15], s[18:19]
	s_mov_b64 s[16:17], s[20:21]
	s_mov_b64 s[18:19], s[22:23]
	s_add_u32 s0, s18, s0
	s_addc_u32 s1, s19, s1
	s_lshl_b32 s42, s56, 8
	s_lshl_b64 s[6:7], s[42:43], 2
	v_readlane_b32 s8, v252, 34
	v_readlane_b32 s9, v252, 35
	s_add_u32 s8, s8, s6
	v_writelane_b32 v255, s6, 41
	s_addc_u32 s9, s9, s7
	s_add_i32 s2, s2, s97
	v_mbcnt_lo_u32_b32 v0, -1, 0
	v_mbcnt_hi_u32_b32 v0, -1, v0
	s_mov_b64 s[4:5], s[78:79]
	v_add_u32_e32 v50, s2, v0
	s_mov_b32 s2, 0x20000
	v_readlane_b32 s10, v252, 36
	v_readlane_b32 s11, v252, 37
	v_readlane_b32 s16, v252, 42
	v_readlane_b32 s17, v252, 43
	v_readlane_b32 s18, v252, 44
	v_readlane_b32 s19, v252, 45
	v_readlane_b32 s20, v252, 46
	v_readlane_b32 s21, v252, 47
	v_readlane_b32 s22, v252, 48
	v_writelane_b32 v255, s7, 42
	v_cmp_gt_i32_e32 vcc, s2, v50
	v_lshlrev_b32_e32 v51, 2, v50
	v_readlane_b32 s12, v252, 38
	v_readlane_b32 s13, v252, 39
	v_readlane_b32 s14, v252, 40
	v_readlane_b32 s15, v252, 41
	v_readlane_b32 s23, v252, 49
	s_mov_b32 s100, 0
	s_cmp_lt_u32 s82, 32
	s_cbranch_scc0 .Lconv_norm
	s_cmp_eq_u32 s89, 0
	s_cbranch_scc0 .Lconv_w1
	s_mov_b64 vcc, 0
	s_branch .Lconv_norm
.Lconv_w1:
	s_cmp_eq_u32 s89, 1
	s_cselect_b32 s100, 1, 0
.Lconv_norm:
	s_and_saveexec_b64 s[10:11], vcc
	v_readlane_b32 s16, v253, 21
	v_readlane_b32 s18, v253, 23
	v_readlane_b32 s17, v253, 22
	v_readlane_b32 s19, v253, 24
	s_mov_b32 s20, 0x1ffff
	s_mov_b32 s21, 0x2040000
	s_movk_i32 s22, 0x7fe
	s_cbranch_execz .LBB0_325
	s_lshl_b32 s42, s56, 4
	s_add_u32 s12, s4, 0x2040000
	s_addc_u32 s13, s5, 0
	v_lshlrev_b32_e32 v52, 2, v50
	s_mov_b64 s[14:15], 0
	v_mov_b32_e32 v53, v50
	s_branch .LBB0_321
.LBB0_320:
	s_or_b64 exec, exec, s[2:3]
	s_cmp_eq_u32 s100, 1
	s_cbranch_scc0 .Lconv_lat
	s_mov_b32 s100, 0
	v_subrev_u32_e32 v53, 64, v53
	v_add_u32_e32 v52, 0xffffff00, v52
	s_branch .LBB0_321
.Lconv_lat:
	v_add_u32_e32 v53, s72, v53
	v_cmp_lt_i32_e32 vcc, s20, v53
	s_or_b64 s[14:15], vcc, s[14:15]
	v_add_u32_e32 v52, s26, v52
	s_andn2_b64 exec, exec, s[14:15]
	s_cbranch_execz .LBB0_325
